# attention d=1 epilogue: partial/gain loads hoisted to one wait and widened to dwordx4 via permlane32_swap; Y stores dwordx4
# speedup vs baseline: 1.0207x; 1.0167x over previous
; template <int MODE> ...
;     ...
;         } else {
;             const float lt = lt0 + L4[row * 8 + head] + L16[row * 8 + head]; const float inv = 1.f / lt; float ss = 0.f;
; #pragma unroll
;             for (int dt = 0; dt < 2; ++dt)
; #pragma unroll
;                 for (int ii = 0; ii < 4; ++ii) { const size_t off = row * 512 + head * 64 + 32 * dt + 8 * ii + 4 * h;
;                     const u32x2 a = *(const u32x2*)(P4 + off), c = *(const u32x2*)(P16 + off);
;                     const float add[4] = {__uint_as_float(a.x << 16) + __uint_as_float(c.x << 16), __uint_as_float(a.x & 0xffff0000u) + __uint_as_float(c.x & 0xffff0000u),
;                                           __uint_as_float(a.y << 16) + __uint_as_float(c.y << 16), __uint_as_float(a.y & 0xffff0000u) + __uint_as_float(c.y & 0xffff0000u)};
; #pragma unroll
;                     for (int e = 0; e < 4; ++e) { const float v = (o[dt][4 * ii + e] + add[e]) * inv; o[dt][4 * ii + e] = v; ss += v * v; } }
.LBB0_617:
	v_and_b32_e32 v33, 64, v135
	v_xor_b32_e32 v32, 32, v135
	v_add_u32_e32 v33, 64, v33
	v_cmp_lt_i32_e32 vcc, v32, v33
	s_nop 1
	v_cndmask_b32_e32 v32, v135, v32, vcc
	v_lshlrev_b32_e32 v38, 2, v32
	ds_bpermute_b32 v32, v38, v138
	s_waitcnt lgkmcnt(0)
	v_add_f32_e32 v36, v138, v32
	v_lshlrev_b64 v[32:33], 5, v[106:107]
	v_lshl_or_b32 v32, s90, 2, v32
	v_lshl_add_u64 v[34:35], s[92:93], 0, v[32:33]
	global_load_dword v34, v[34:35], off
	v_lshl_add_u64 v[32:33], s[94:95], 0, v[32:33]
	global_load_dword v32, v[32:33], off
	v_lshlrev_b32_e32 v176, 9, v106
	v_or3_b32 v176, v176, v98, s83
	v_lshlrev_b32_e32 v176, 1, v176
	v_and_b32_e32 v232, 32, v135
	v_lshrrev_b32_e32 v232, 2, v232
	v_mov_b32_e32 v233, 0
	v_add_u32_e32 v176, v176, v232
	v_or_b32_e32 v225, s83, v98
	v_lshlrev_b32_e32 v225, 2, v225
	v_readlane_b32 s100, v235, 24
	v_readlane_b32 s101, v235, 25
	global_load_dwordx4 v[144:147], v176, s[72:73] offset:0
	global_load_dwordx4 v[148:151], v176, s[72:73] offset:32
	global_load_dwordx4 v[152:155], v176, s[72:73] offset:64
	global_load_dwordx4 v[156:159], v176, s[72:73] offset:96
	global_load_dwordx4 v[160:163], v176, s[74:75] offset:0
	global_load_dwordx4 v[164:167], v176, s[74:75] offset:32
	global_load_dwordx4 v[168:171], v176, s[74:75] offset:64
	global_load_dwordx4 v[172:175], v176, s[74:75] offset:96
	s_nop 1
	global_load_dwordx4 v[192:195], v225, s[100:101] offset:0
	global_load_dwordx4 v[196:199], v225, s[100:101] offset:32
	global_load_dwordx4 v[200:203], v225, s[100:101] offset:64
	global_load_dwordx4 v[204:207], v225, s[100:101] offset:96
	global_load_dwordx4 v[208:211], v225, s[100:101] offset:128
	global_load_dwordx4 v[212:215], v225, s[100:101] offset:160
	global_load_dwordx4 v[216:219], v225, s[100:101] offset:192
	global_load_dwordx4 v[220:223], v225, s[100:101] offset:224
	s_waitcnt vmcnt(0) lgkmcnt(0)
	v_permlane32_swap_b32_e32 v144, v146
	v_permlane32_swap_b32_e32 v145, v147
	v_permlane32_swap_b32_e32 v148, v150
	v_permlane32_swap_b32_e32 v149, v151
	v_permlane32_swap_b32_e32 v152, v154
	v_permlane32_swap_b32_e32 v153, v155
	v_permlane32_swap_b32_e32 v156, v158
	v_permlane32_swap_b32_e32 v157, v159
	v_permlane32_swap_b32_e32 v160, v162
	v_permlane32_swap_b32_e32 v161, v163
	v_permlane32_swap_b32_e32 v164, v166
	v_permlane32_swap_b32_e32 v165, v167
	v_permlane32_swap_b32_e32 v168, v170
	v_permlane32_swap_b32_e32 v169, v171
	v_permlane32_swap_b32_e32 v172, v174
	v_permlane32_swap_b32_e32 v173, v175
	v_add_f32_e32 v34, v34, v36
	v_add_f32_e32 v32, v32, v34
	v_div_scale_f32 v33, s[0:1], v32, v32, 1.0
	v_rcp_f32_e32 v34, v33
	s_mov_b32 s0, 0x800000
	v_fma_f32 v35, -v33, v34, 1.0
	v_fmac_f32_e32 v34, v35, v34
	v_div_scale_f32 v35, vcc, 1.0, v32, 1.0
	v_mul_f32_e32 v36, v35, v34
	v_fma_f32 v37, -v33, v36, v35
	v_fmac_f32_e32 v36, v37, v34
	v_fma_f32 v33, -v33, v36, v35
	v_div_fmas_f32 v33, v33, v34, v36
	v_lshlrev_b64 v[34:35], 9, v[106:107]
	v_or3_b32 v35, v35, 0, 0
	v_or3_b32 v34, v34, v98, s83
	v_lshlrev_b64 v[34:35], 1, v[34:35]
	v_lshl_add_u64 v[36:37], s[72:73], 0, v[34:35]
	v_lshl_add_u64 v[40:41], s[74:75], 0, v[34:35]
	v_mov_b32_e32 v36, v144
	v_mov_b32_e32 v37, v145
	v_div_fixup_f32 v32, v33, v32, 1.0
	v_mov_b32_e32 v40, v160
	v_mov_b32_e32 v41, v161
	s_waitcnt vmcnt(0) lgkmcnt(0)
	v_lshlrev_b32_e32 v33, 16, v36
	v_and_b32_e32 v36, 0xffff0000, v36
	v_lshlrev_b32_e32 v39, 16, v40
	v_add_f32_e32 v33, v39, v33
	v_and_b32_e32 v39, 0xffff0000, v40
	v_add_f32_e32 v36, v39, v36
	v_lshlrev_b32_e32 v39, 16, v37
	v_lshlrev_b32_e32 v40, 16, v41
	v_add_f32_e32 v39, v40, v39
	v_and_b32_e32 v40, 0xffff0000, v41
	v_and_b32_e32 v37, 0xffff0000, v37
	v_add_f32_e32 v37, v40, v37
	v_add_f32_e32 v17, v17, v36
	v_add_f32_e32 v19, v19, v37
	v_or_b32_e32 v36, 16, v34
	v_mov_b32_e32 v37, v35
	v_lshl_add_u64 v[40:41], s[72:73], 0, v[36:37]
	v_lshl_add_u64 v[36:37], s[74:75], 0, v[36:37]
	v_mov_b32_e32 v40, v146
	v_mov_b32_e32 v41, v147
	v_add_f32_e32 v16, v16, v33
	v_mov_b32_e32 v36, v162
	v_mov_b32_e32 v37, v163
	v_add_f32_e32 v18, v18, v39
	v_mul_f32_e32 v17, v32, v17
	v_mul_f32_e32 v16, v32, v16
	v_mul_f32_e32 v42, v17, v17
	v_fmac_f32_e32 v42, v16, v16
	v_mul_f32_e32 v18, v32, v18
	v_fmac_f32_e32 v42, v18, v18
	v_mul_f32_e32 v19, v32, v19
	v_fmac_f32_e32 v42, v19, v19
	s_waitcnt vmcnt(0) lgkmcnt(0)
	v_lshlrev_b32_e32 v33, 16, v40
	v_lshlrev_b32_e32 v39, 16, v36
	v_add_f32_e32 v33, v39, v33
	v_and_b32_e32 v36, 0xffff0000, v36
	v_and_b32_e32 v39, 0xffff0000, v40
	v_add_f32_e32 v36, v36, v39
	v_lshlrev_b32_e32 v39, 16, v41
	v_lshlrev_b32_e32 v40, 16, v37
	v_add_f32_e32 v39, v40, v39
	v_and_b32_e32 v37, 0xffff0000, v37
	v_and_b32_e32 v40, 0xffff0000, v41
	v_add_f32_e32 v37, v37, v40
	v_add_f32_e32 v21, v21, v36
	v_add_f32_e32 v23, v23, v37
	v_or_b32_e32 v36, 32, v34
	v_mov_b32_e32 v37, v35
	v_lshl_add_u64 v[40:41], s[72:73], 0, v[36:37]
	v_lshl_add_u64 v[36:37], s[74:75], 0, v[36:37]
	v_mov_b32_e32 v40, v148
	v_mov_b32_e32 v41, v149
	v_add_f32_e32 v20, v20, v33
	v_mov_b32_e32 v36, v164
	v_mov_b32_e32 v37, v165
	v_add_f32_e32 v22, v22, v39
	v_mul_f32_e32 v20, v32, v20
	v_fmac_f32_e32 v42, v20, v20
	v_mul_f32_e32 v21, v32, v21
	v_fmac_f32_e32 v42, v21, v21
	v_mul_f32_e32 v22, v32, v22
	v_fmac_f32_e32 v42, v22, v22
	v_mul_f32_e32 v23, v32, v23
	v_fmac_f32_e32 v42, v23, v23
	s_waitcnt vmcnt(0) lgkmcnt(0)
; template <int MODE> ...
;     ...
;                 for (int ii = 0; ii < 4; ++ii) { const size_t off = row * 512 + head * 64 + 32 * dt + 8 * ii + 4 * h;
;                     const u32x2 a = *(const u32x2*)(P4 + off), c = *(const u32x2*)(P16 + off);
;                     const float add[4] = {__uint_as_float(a.x << 16) + __uint_as_float(c.x << 16), __uint_as_float(a.x & 0xffff0000u) + __uint_as_float(c.x & 0xffff0000u),
;                                           __uint_as_float(a.y << 16) + __uint_as_float(c.y << 16), __uint_as_float(a.y & 0xffff0000u) + __uint_as_float(c.y & 0xffff0000u)};
; #pragma unroll
;                     for (int e = 0; e < 4; ++e) { const float v = (o[dt][4 * ii + e] + add[e]) * inv; o[dt][4 * ii + e] = v; ss += v * v; } }
;             ss += __shfl_xor(ss, 32);
	v_lshlrev_b32_e32 v33, 16, v40
	v_lshlrev_b32_e32 v39, 16, v36
	v_add_f32_e32 v33, v39, v33
	v_and_b32_e32 v36, 0xffff0000, v36
	v_and_b32_e32 v39, 0xffff0000, v40
	v_add_f32_e32 v39, v36, v39
	v_lshlrev_b32_e32 v36, 16, v41
	v_lshlrev_b32_e32 v40, 16, v37
	v_add_f32_e32 v40, v40, v36
	v_and_b32_e32 v36, 0xffff0000, v37
	v_and_b32_e32 v37, 0xffff0000, v41
	v_add_f32_e32 v24, v24, v33
	v_add_f32_e32 v37, v36, v37
	v_mul_f32_e32 v36, v32, v24
	v_add_f32_e32 v24, v25, v39
	v_mul_f32_e32 v33, v32, v24
	v_add_f32_e32 v24, v26, v40
	v_mul_f32_e32 v25, v32, v24
	v_add_f32_e32 v24, v27, v37
	v_or_b32_e32 v26, 48, v34
	v_mov_b32_e32 v27, v35
	v_lshl_add_u64 v[40:41], s[72:73], 0, v[26:27]
	v_lshl_add_u64 v[26:27], s[74:75], 0, v[26:27]
	v_mov_b32_e32 v40, v150
	v_mov_b32_e32 v41, v151
	v_fmac_f32_e32 v42, v36, v36
	v_mov_b32_e32 v26, v166
	v_mov_b32_e32 v27, v167
	v_fmac_f32_e32 v42, v33, v33
	v_fmac_f32_e32 v42, v25, v25
	v_mul_f32_e32 v24, v32, v24
	v_fmac_f32_e32 v42, v24, v24
	s_waitcnt vmcnt(0) lgkmcnt(0)
	v_lshlrev_b32_e32 v37, 16, v40
	v_lshlrev_b32_e32 v39, 16, v26
	v_add_f32_e32 v37, v39, v37
	v_and_b32_e32 v26, 0xffff0000, v26
	v_and_b32_e32 v39, 0xffff0000, v40
	v_add_f32_e32 v26, v26, v39
	v_lshlrev_b32_e32 v39, 16, v41
	v_lshlrev_b32_e32 v40, 16, v27
	v_add_f32_e32 v39, v40, v39
	v_and_b32_e32 v27, 0xffff0000, v27
	v_and_b32_e32 v40, 0xffff0000, v41
	v_add_f32_e32 v26, v29, v26
	v_add_f32_e32 v40, v27, v40
	v_add_f32_e32 v27, v28, v37
	v_mul_f32_e32 v28, v32, v26
	v_add_f32_e32 v26, v30, v39
	v_mul_f32_e32 v37, v32, v27
	v_mul_f32_e32 v27, v32, v26
	v_add_f32_e32 v26, v31, v40
	v_or_b32_e32 v30, 64, v34
	v_mov_b32_e32 v31, v35
	v_lshl_add_u64 v[40:41], s[72:73], 0, v[30:31]
	v_lshl_add_u64 v[30:31], s[74:75], 0, v[30:31]
	v_mov_b32_e32 v40, v152
	v_mov_b32_e32 v41, v153
	v_fmac_f32_e32 v42, v37, v37
	v_mov_b32_e32 v30, v168
	v_mov_b32_e32 v31, v169
	v_fmac_f32_e32 v42, v28, v28
	v_fmac_f32_e32 v42, v27, v27
	v_mul_f32_e32 v26, v32, v26
	v_fmac_f32_e32 v42, v26, v26
	s_waitcnt vmcnt(0) lgkmcnt(0)
	v_lshlrev_b32_e32 v29, 16, v40
	v_lshlrev_b32_e32 v39, 16, v30
	v_add_f32_e32 v29, v39, v29
	v_and_b32_e32 v30, 0xffff0000, v30
	v_and_b32_e32 v39, 0xffff0000, v40
	v_add_f32_e32 v30, v30, v39
	v_lshlrev_b32_e32 v39, 16, v41
	v_lshlrev_b32_e32 v40, 16, v31
	v_add_f32_e32 v40, v40, v39
	v_and_b32_e32 v31, 0xffff0000, v31
	v_and_b32_e32 v39, 0xffff0000, v41
	v_add_f32_e32 v0, v0, v29
	v_add_f32_e32 v41, v31, v39
	v_mul_f32_e32 v39, v32, v0
	v_add_f32_e32 v0, v1, v30
	v_mul_f32_e32 v31, v32, v0
	v_add_f32_e32 v0, v2, v40
	v_mul_f32_e32 v30, v32, v0
	v_add_f32_e32 v0, v3, v41
	v_mul_f32_e32 v29, v32, v0
	v_or_b32_e32 v0, 0x50, v34
	v_mov_b32_e32 v1, v35
	v_lshl_add_u64 v[2:3], s[72:73], 0, v[0:1]
	v_lshl_add_u64 v[0:1], s[74:75], 0, v[0:1]
	v_mov_b32_e32 v2, v154
	v_mov_b32_e32 v3, v155
	v_fmac_f32_e32 v42, v39, v39
	v_mov_b32_e32 v0, v170
	v_mov_b32_e32 v1, v171
	v_fmac_f32_e32 v42, v31, v31
	v_fmac_f32_e32 v42, v30, v30
	v_fmac_f32_e32 v42, v29, v29
	s_waitcnt vmcnt(0) lgkmcnt(0)
	v_lshlrev_b32_e32 v40, 16, v2
	v_and_b32_e32 v2, 0xffff0000, v2
	v_lshlrev_b32_e32 v41, 16, v0
	v_and_b32_e32 v0, 0xffff0000, v0
	v_add_f32_e32 v40, v41, v40
	v_add_f32_e32 v43, v0, v2
	v_lshlrev_b32_e32 v0, 16, v1
	v_lshlrev_b32_e32 v2, 16, v3
	v_and_b32_e32 v1, 0xffff0000, v1
	v_and_b32_e32 v3, 0xffff0000, v3
	v_add_f32_e32 v4, v4, v40
	v_pk_add_f32 v[0:1], v[2:3], v[0:1]
	v_mul_f32_e32 v41, v32, v4
	v_add_f32_e32 v4, v5, v43
	v_pk_add_f32 v[0:1], v[6:7], v[0:1]
	v_fmac_f32_e32 v42, v41, v41
	v_mul_f32_e32 v40, v32, v4
	v_pk_mul_f32 v[4:5], v[32:33], v[0:1] op_sel_hi:[0,1]
	v_fmac_f32_e32 v42, v40, v40
	v_pk_mul_f32 v[0:1], v[4:5], v[4:5]
	s_nop 0
	v_add_f32_e32 v0, v0, v42
	v_add_f32_e32 v44, v1, v0
	v_or_b32_e32 v0, 0x60, v34
	v_mov_b32_e32 v1, v35
	v_lshl_add_u64 v[2:3], s[72:73], 0, v[0:1]
	v_lshl_add_u64 v[0:1], s[74:75], 0, v[0:1]
	v_mov_b32_e32 v2, v156
	v_mov_b32_e32 v3, v157
	v_or_b32_e32 v34, 0x70, v34
	v_mov_b32_e32 v0, v172
	v_mov_b32_e32 v1, v173
	s_waitcnt vmcnt(0) lgkmcnt(0)
	v_lshlrev_b32_e32 v42, 16, v2
	v_and_b32_e32 v43, 0xffff0000, v2
	v_lshlrev_b32_e32 v6, 16, v0
	v_and_b32_e32 v7, 0xffff0000, v0
	v_pk_add_f32 v[6:7], v[42:43], v[6:7]
	v_lshlrev_b32_e32 v0, 16, v1
	v_pk_add_f32 v[6:7], v[8:9], v[6:7]
	v_lshlrev_b32_e32 v2, 16, v3
	v_and_b32_e32 v1, 0xffff0000, v1
	v_and_b32_e32 v3, 0xffff0000, v3
	v_pk_mul_f32 v[8:9], v[32:33], v[6:7] op_sel_hi:[0,1]
	v_pk_mul_f32 v[6:7], v[8:9], v[8:9]
	v_pk_add_f32 v[0:1], v[2:3], v[0:1]
	v_add_f32_e32 v6, v6, v44
	v_pk_add_f32 v[0:1], v[10:11], v[0:1]
	v_add_f32_e32 v42, v7, v6
	v_pk_mul_f32 v[6:7], v[32:33], v[0:1] op_sel_hi:[0,1]
	v_pk_mul_f32 v[0:1], v[6:7], v[6:7]
	v_lshl_add_u64 v[2:3], s[74:75], 0, v[34:35]
	v_add_f32_e32 v0, v0, v42
	v_add_f32_e32 v42, v1, v0
	v_lshl_add_u64 v[0:1], s[72:73], 0, v[34:35]
	v_mov_b32_e32 v0, v158
	v_mov_b32_e32 v1, v159
	s_nop 0
	v_mov_b32_e32 v2, v174
	v_mov_b32_e32 v3, v175
	s_waitcnt vmcnt(0) lgkmcnt(0)
	v_lshlrev_b32_e32 v34, 16, v0
	v_and_b32_e32 v35, 0xffff0000, v0
	v_lshlrev_b32_e32 v10, 16, v2
	v_and_b32_e32 v11, 0xffff0000, v2
	v_pk_add_f32 v[10:11], v[34:35], v[10:11]
	v_or_b32_e32 v35, s83, v98
	v_pk_add_f32 v[10:11], v[12:13], v[10:11]
	v_lshlrev_b32_e32 v34, 2, v35
	v_pk_mul_f32 v[10:11], v[32:33], v[10:11] op_sel_hi:[0,1]
	v_pk_mul_f32 v[12:13], v[10:11], v[10:11]
	v_lshlrev_b32_e32 v96, 1, v35
	v_add_f32_e32 v0, v12, v42
	v_add_f32_e32 v2, v13, v0
	v_and_b32_e32 v13, 0xffff0000, v1
	v_lshlrev_b32_e32 v12, 16, v1
	v_and_b32_e32 v1, 0xffff0000, v3
	v_lshlrev_b32_e32 v0, 16, v3
	v_pk_add_f32 v[0:1], v[12:13], v[0:1]
	s_nop 0
	v_pk_add_f32 v[0:1], v[14:15], v[0:1]
	s_nop 0
	v_pk_mul_f32 v[12:13], v[32:33], v[0:1] op_sel_hi:[0,1]
	v_pk_mul_f32 v[0:1], v[12:13], v[12:13]
	s_nop 0
	v_add_f32_e32 v0, v0, v2
	v_add_f32_e32 v0, v1, v0
	ds_bpermute_b32 v1, v38, v0
	s_waitcnt lgkmcnt(0)
; __device__ __forceinline__ unsigned pk2(float lo, float hi) { return pg8::cvt_pk_bf16(lo, hi); }
; template <int MODE> ...
;     ...
;             const float rr = rsqrtf(ss * (1.f / 64.f) + EPS);
; #pragma unroll
;             for (int dt = 0; dt < 2; ++dt)
; #pragma unroll
;                 for (int ii = 0; ii < 4; ++ii) { const int d0 = head * 64 + 32 * dt + 8 * ii + 4 * h; const f32x4 gv = *(const f32x4*)(gain + d0);
;                     u32x2 w; w.x = pk2(o[dt][4 * ii] * rr * gv[0], o[dt][4 * ii + 1] * rr * gv[1]); w.y = pk2(o[dt][4 * ii + 2] * rr * gv[2], o[dt][4 * ii + 3] * rr * gv[3]);
;                     *(u32x2*)(Y + row * DM + d0) = w; }
	v_add_f32_e32 v0, v0, v1
	v_fmamk_f32 v0, v0, 0x3c800000, v133
	v_cmp_gt_f32_e32 vcc, s0, v0
	v_mul_f32_e32 v1, 0x4b800000, v0
	v_readlane_b32 s0, v235, 2
	v_cndmask_b32_e32 v0, v0, v1, vcc
	v_rsq_f32_e32 v0, v0
	v_readlane_b32 s1, v235, 3
	v_readlane_b32 s2, v235, 4
	v_readlane_b32 s3, v235, 5
	v_mul_f32_e32 v1, 0x45800000, v0
	v_cndmask_b32_e32 v32, v0, v1, vcc
	v_lshlrev_b64 v[0:1], 11, v[106:107]
	v_lshl_add_u64 v[14:15], s[0:1], 0, v[0:1]
	s_mov_b32 s1, s77
	v_readlane_b32 s76, v235, 14
	v_readlane_b32 s86, v235, 24
	v_readlane_b32 s87, v235, 25
	v_mul_f32_e32 v16, v16, v32
	v_mul_f32_e32 v8, v8, v32
	v_readlane_b32 s0, v235, 41
	v_readlane_b32 s77, v235, 15
	s_add_i32 s33, s33, s0
	v_mov_b32_e32 v0, v192
	v_mov_b32_e32 v1, v193
	v_mov_b32_e32 v2, v194
	v_mov_b32_e32 v3, v195
	s_mov_b32 s77, s1
	s_cmpk_gt_i32 s33, 0x1fff
	v_readlane_b32 s78, v235, 16
	v_readlane_b32 s79, v235, 17
	v_readlane_b32 s80, v235, 18
	v_readlane_b32 s81, v235, 19
	v_readlane_b32 s82, v235, 20
	v_readlane_b32 s83, v235, 21
	v_readlane_b32 s84, v235, 22
	v_readlane_b32 s85, v235, 23
	v_readlane_b32 s88, v235, 26
	v_readlane_b32 s89, v235, 27
	v_readlane_b32 s90, v235, 28
	v_readlane_b32 s91, v235, 29
	s_nop 0
	v_mul_f32_e32 v0, v0, v16
	v_mul_f32_e32 v16, v17, v32
	v_mul_f32_e32 v1, v1, v16
	v_cvt_pk_bf16_f32 v180, v0, v1
	v_mul_f32_e32 v0, v18, v32
	v_mul_f32_e32 v1, v19, v32
	v_mul_f32_e32 v0, v2, v0
	v_mul_f32_e32 v1, v3, v1
	v_cvt_pk_bf16_f32 v181, v0, v1
	v_lshl_add_u64 v[0:1], v[14:15], 0, v[96:97]
	s_nop 0
	v_mov_b32_e32 v14, v196
	v_mov_b32_e32 v15, v197
	v_mov_b32_e32 v16, v198
	v_mov_b32_e32 v17, v199
	v_mul_f32_e32 v2, v20, v32
	v_mul_f32_e32 v3, v21, v32
	s_nop 0
	v_mul_f32_e32 v2, v14, v2
	v_mul_f32_e32 v3, v15, v3
	v_cvt_pk_bf16_f32 v182, v2, v3
	v_mul_f32_e32 v3, v22, v32
	v_mul_f32_e32 v3, v16, v3
	v_mul_f32_e32 v14, v23, v32
	v_mul_f32_e32 v14, v17, v14
	v_cvt_pk_bf16_f32 v183, v3, v14
	s_nop 1
	v_permlane32_swap_b32_e32 v180, v182
	v_permlane32_swap_b32_e32 v181, v183
	v_lshl_add_u64 v[226:227], v[0:1], 0, v[232:233]
	global_store_dwordx4 v[226:227], v[180:183], off offset:0
	v_mov_b32_e32 v14, v200
	v_mov_b32_e32 v15, v201
	v_mov_b32_e32 v16, v202
	v_mov_b32_e32 v17, v203
	v_mul_f32_e32 v2, v36, v32
	v_mul_f32_e32 v3, v33, v32
	s_nop 0
	v_mul_f32_e32 v2, v14, v2
	v_mul_f32_e32 v3, v15, v3
	v_cvt_pk_bf16_f32 v228, v2, v3
	v_mul_f32_e32 v3, v25, v32
	v_mul_f32_e32 v3, v16, v3
	v_mul_f32_e32 v14, v24, v32
	v_mul_f32_e32 v14, v17, v14
	v_cvt_pk_bf16_f32 v229, v3, v14
	s_nop 0
	v_mov_b32_e32 v14, v204
	v_mov_b32_e32 v15, v205
	v_mov_b32_e32 v16, v206
	v_mov_b32_e32 v17, v207
	v_mul_f32_e32 v2, v37, v32
	v_mul_f32_e32 v3, v28, v32
	s_nop 0
	v_mul_f32_e32 v2, v14, v2
	v_mul_f32_e32 v3, v15, v3
	v_cvt_pk_bf16_f32 v230, v2, v3
	v_mul_f32_e32 v3, v27, v32
	v_mul_f32_e32 v3, v16, v3
	v_mul_f32_e32 v14, v26, v32
	v_mul_f32_e32 v14, v17, v14
	v_cvt_pk_bf16_f32 v231, v3, v14
	s_nop 1
	v_permlane32_swap_b32_e32 v228, v230
	v_permlane32_swap_b32_e32 v229, v231
	v_lshl_add_u64 v[226:227], v[0:1], 0, v[232:233]
	global_store_dwordx4 v[226:227], v[228:231], off offset:32
	v_mov_b32_e32 v14, v208
	v_mov_b32_e32 v15, v209
	v_mov_b32_e32 v16, v210
	v_mov_b32_e32 v17, v211
	v_mul_f32_e32 v2, v39, v32
	v_mul_f32_e32 v3, v31, v32
	s_nop 0
	v_mul_f32_e32 v2, v14, v2
	v_mul_f32_e32 v3, v15, v3
	v_cvt_pk_bf16_f32 v180, v2, v3
	v_mul_f32_e32 v3, v30, v32
	v_mul_f32_e32 v3, v16, v3
	v_mul_f32_e32 v14, v29, v32
	v_mul_f32_e32 v14, v17, v14
	v_cvt_pk_bf16_f32 v181, v3, v14
	s_nop 0
	v_mov_b32_e32 v14, v212
	v_mov_b32_e32 v15, v213
	v_mov_b32_e32 v16, v214
	v_mov_b32_e32 v17, v215
	v_mul_f32_e32 v2, v41, v32
	v_mul_f32_e32 v3, v40, v32
	s_nop 0
	v_mul_f32_e32 v2, v14, v2
	v_mul_f32_e32 v3, v15, v3
	v_cvt_pk_bf16_f32 v182, v2, v3
	v_mul_f32_e32 v3, v4, v32
	v_mul_f32_e32 v3, v16, v3
	v_mul_f32_e32 v4, v5, v32
	v_mul_f32_e32 v4, v17, v4
	v_cvt_pk_bf16_f32 v183, v3, v4
	s_nop 1
	v_permlane32_swap_b32_e32 v180, v182
	v_permlane32_swap_b32_e32 v181, v183
	v_lshl_add_u64 v[226:227], v[0:1], 0, v[232:233]
	global_store_dwordx4 v[226:227], v[180:183], off offset:64
	v_mov_b32_e32 v2, v216
	v_mov_b32_e32 v3, v217
	v_mov_b32_e32 v4, v218
	v_mov_b32_e32 v5, v219
	s_nop 0
	v_mul_f32_e32 v2, v2, v8
	v_mul_f32_e32 v8, v9, v32
	v_mul_f32_e32 v3, v3, v8
	v_cvt_pk_bf16_f32 v228, v2, v3
	v_mul_f32_e32 v3, v6, v32
	v_mul_f32_e32 v3, v4, v3
	v_mul_f32_e32 v4, v7, v32
	v_mul_f32_e32 v4, v5, v4
	v_cvt_pk_bf16_f32 v229, v3, v4
	s_nop 0
	v_mov_b32_e32 v2, v220
	v_mov_b32_e32 v3, v221
	v_mov_b32_e32 v4, v222
	v_mov_b32_e32 v5, v223
	v_mul_f32_e32 v6, v10, v32
	s_nop 0
	v_mul_f32_e32 v2, v2, v6
	v_mul_f32_e32 v6, v11, v32
	v_mul_f32_e32 v3, v3, v6
	v_cvt_pk_bf16_f32 v230, v2, v3
	v_mul_f32_e32 v3, v12, v32
	v_mul_f32_e32 v3, v4, v3
	v_mul_f32_e32 v4, v13, v32
	v_mul_f32_e32 v4, v5, v4
	v_cvt_pk_bf16_f32 v231, v3, v4
	s_nop 1
	v_permlane32_swap_b32_e32 v228, v230
	v_permlane32_swap_b32_e32 v229, v231
	v_lshl_add_u64 v[226:227], v[0:1], 0, v[232:233]
	global_store_dwordx4 v[226:227], v[228:231], off offset:96
	s_cbranch_scc1 .LBB0_627
